# P5 state scan: both per-thread iterations issue their 62 loads up front, one wait, then the two scan chains back to back
# speedup vs baseline: 1.0006x; 1.0006x over previous
; __device__ __forceinline__ unsigned cvtpk(float lo, float hi) { f32x2_t v = {lo, hi}; bf16x2_t b = __builtin_convertvector(v, bf16x2_t); return __builtin_bit_cast(unsigned, b); }
; __device__ __forceinline__ float lg2gamma(int h) { return log2f(1.0f - exp2f(-5.0f - (float)h)); }
; __global__ void __launch_bounds__(512, 2) mk_fwd(Args a) {
;     ...
;         for (int idx = bid * 512 + tid; idx < 16 * 16384; idx += G * 512) {
;             const int bh = idx >> 14, ed = idx & 16383, h = bh & 7;
;             const float lg = lg2gamma(h), gm = exp2f(lg), gC = exp2f(128.0f * lg);
;             float v[32];
; #pragma unroll
;             for (int n = 0; n < 32; ++n) v[n] = STATE[(size_t)(bh * 32 + n) * 16384 + ed];
;             float run = 0.f;
; #pragma unroll
;             for (int n = 0; n < 32; ++n) { SPREV[(size_t)(bh * 32 + n) * 16384 + ed] = (bf16_t)(cvtpk(gm * run, 0.f) & 0xffffu); run = run * gC + v[n]; }
.LBB0_1147:
	s_cmp_lt_i32 s88, 6
	s_cselect_b64 s[0:1], -1, 0
	s_add_u32 s34, s84, 0x18500000
	s_addc_u32 s35, s85, 0
	s_and_b64 s[2:3], s[0:1], s[2:3]
	s_andn2_b64 vcc, exec, s[2:3]
	s_cbranch_vccnz .LBB0_1152
	v_lshl_add_u32 v4, s87, 9, v1
	s_mov_b32 s2, 0x40000
	v_cmp_gt_i32_e32 vcc, s2, v4
	s_and_saveexec_b64 s[2:3], vcc
	s_cbranch_execz .LBB0_1151
	s_lshl_b32 s6, s86, 9
	s_mov_b64 s[4:5], 0
	s_mov_b32 s7, 0xc2fc0000
	v_mov_b32_e32 v5, 0x42800000
	v_not_b32_e32 v6, 63
	s_mov_b32 s8, 0x800000
	s_waitcnt lgkmcnt(0)
	v_mov_b32_e32 v7, 0x42000000
	v_mov_b32_e32 v3, 0
	s_mov_b32 s9, 0x3ffff
	s_mov_b64 s[100:101], 0x1000000
	s_mov_b64 s[98:99], 0x800000
.LBB0_1150:
	v_ashrrev_i32_e32 v2, 14, v4
	v_and_b32_e32 v8, 0x3fff, v4
	v_lshlrev_b32_e32 v10, 5, v2
	v_and_b32_e32 v9, 7, v2
	v_lshlrev_b32_e32 v2, 2, v8
	v_ashrrev_i32_e32 v11, 31, v10
	v_lshl_add_u64 v[12:13], s[52:53], 0, v[2:3]
	v_lshlrev_b64 v[74:75], 16, v[10:11]
	v_lshl_add_u64 v[74:75], v[12:13], 0, v[74:75]
	v_lshl_add_u64 v[224:225], v[74:75], 0, s[100:101]
	global_load_dword v128, v[74:75], off
	global_load_dword v192, v[224:225], off
	v_or_b32_e32 v14, 1, v10
	v_or_b32_e32 v16, 2, v10
	v_or_b32_e32 v18, 3, v10
	v_cvt_f32_ubyte0_e32 v9, v9
	v_or_b32_e32 v20, 4, v10
	v_or_b32_e32 v22, 5, v10
	v_or_b32_e32 v24, 6, v10
	v_or_b32_e32 v26, 7, v10
	v_or_b32_e32 v28, 8, v10
	v_or_b32_e32 v30, 9, v10
	v_or_b32_e32 v32, 10, v10
	v_or_b32_e32 v34, 11, v10
	v_or_b32_e32 v36, 12, v10
	v_or_b32_e32 v38, 13, v10
	v_or_b32_e32 v40, 14, v10
	v_or_b32_e32 v42, 15, v10
	v_or_b32_e32 v44, 16, v10
	v_or_b32_e32 v46, 17, v10
	v_or_b32_e32 v48, 18, v10
	v_or_b32_e32 v50, 19, v10
	v_or_b32_e32 v52, 20, v10
	v_or_b32_e32 v54, 21, v10
	v_or_b32_e32 v56, 22, v10
	v_or_b32_e32 v58, 23, v10
	v_or_b32_e32 v60, 24, v10
	v_or_b32_e32 v62, 25, v10
	v_or_b32_e32 v64, 26, v10
	v_or_b32_e32 v66, 27, v10
	v_or_b32_e32 v68, 28, v10
	v_or_b32_e32 v70, 29, v10
	v_or_b32_e32 v72, 30, v10
	v_lshlrev_b32_e32 v2, 1, v8
	v_or_b32_e32 v8, 31, v10
	v_ashrrev_i32_e32 v15, 31, v14
	v_ashrrev_i32_e32 v17, 31, v16
	v_ashrrev_i32_e32 v19, 31, v18
	v_sub_f32_e32 v122, 0xc0a00000, v9
	v_ashrrev_i32_e32 v21, 31, v20
	v_ashrrev_i32_e32 v23, 31, v22
	v_ashrrev_i32_e32 v25, 31, v24
	v_ashrrev_i32_e32 v27, 31, v26
	v_ashrrev_i32_e32 v29, 31, v28
	v_ashrrev_i32_e32 v31, 31, v30
	v_ashrrev_i32_e32 v33, 31, v32
	v_ashrrev_i32_e32 v35, 31, v34
	v_ashrrev_i32_e32 v37, 31, v36
	v_ashrrev_i32_e32 v39, 31, v38
	v_ashrrev_i32_e32 v41, 31, v40
	v_ashrrev_i32_e32 v43, 31, v42
	v_ashrrev_i32_e32 v45, 31, v44
	v_ashrrev_i32_e32 v47, 31, v46
	v_ashrrev_i32_e32 v49, 31, v48
	v_ashrrev_i32_e32 v51, 31, v50
	v_ashrrev_i32_e32 v53, 31, v52
	v_ashrrev_i32_e32 v55, 31, v54
	v_ashrrev_i32_e32 v57, 31, v56
	v_ashrrev_i32_e32 v59, 31, v58
	v_ashrrev_i32_e32 v61, 31, v60
	v_ashrrev_i32_e32 v63, 31, v62
	v_ashrrev_i32_e32 v65, 31, v64
	v_ashrrev_i32_e32 v67, 31, v66
	v_ashrrev_i32_e32 v69, 31, v68
	v_ashrrev_i32_e32 v71, 31, v70
	v_ashrrev_i32_e32 v73, 31, v72
	v_ashrrev_i32_e32 v9, 31, v8
	v_lshlrev_b64 v[78:79], 16, v[14:15]
	v_lshlrev_b64 v[80:81], 16, v[16:17]
	v_lshlrev_b64 v[82:83], 16, v[18:19]
	v_lshl_add_u64 v[76:77], s[34:35], 0, v[2:3]
	v_lshlrev_b64 v[10:11], 15, v[10:11]
	v_lshlrev_b64 v[84:85], 16, v[20:21]
	v_lshlrev_b64 v[86:87], 16, v[22:23]
	v_lshlrev_b64 v[88:89], 16, v[24:25]
	v_lshlrev_b64 v[90:91], 16, v[26:27]
	v_lshlrev_b64 v[92:93], 16, v[28:29]
	v_lshlrev_b64 v[94:95], 16, v[30:31]
	v_lshlrev_b64 v[96:97], 16, v[32:33]
	v_lshlrev_b64 v[98:99], 16, v[34:35]
	v_lshlrev_b64 v[100:101], 16, v[36:37]
	v_lshlrev_b64 v[102:103], 16, v[38:39]
	v_lshlrev_b64 v[104:105], 16, v[40:41]
	v_lshlrev_b64 v[106:107], 16, v[42:43]
	v_lshlrev_b64 v[108:109], 16, v[44:45]
	v_lshlrev_b64 v[110:111], 16, v[46:47]
	v_lshlrev_b64 v[112:113], 16, v[48:49]
	v_lshlrev_b64 v[114:115], 16, v[50:51]
	v_lshlrev_b64 v[116:117], 16, v[52:53]
	v_lshlrev_b64 v[118:119], 16, v[54:55]
	v_lshlrev_b64 v[120:121], 16, v[56:57]
	v_lshlrev_b64 v[124:125], 16, v[58:59]
	v_lshlrev_b64 v[126:127], 16, v[60:61]
	v_lshlrev_b64 v[130:131], 16, v[62:63]
	v_lshlrev_b64 v[132:133], 16, v[64:65]
	v_lshlrev_b64 v[134:135], 16, v[66:67]
	v_lshlrev_b64 v[136:137], 16, v[68:69]
	v_lshlrev_b64 v[138:139], 16, v[70:71]
	v_lshlrev_b64 v[140:141], 16, v[72:73]
	v_lshlrev_b64 v[14:15], 15, v[14:15]
	v_lshlrev_b64 v[16:17], 15, v[16:17]
	v_lshlrev_b64 v[18:19], 15, v[18:19]
	v_lshlrev_b64 v[20:21], 15, v[20:21]
	v_lshlrev_b64 v[22:23], 15, v[22:23]
	v_lshlrev_b64 v[24:25], 15, v[24:25]
	v_lshlrev_b64 v[26:27], 15, v[26:27]
	v_lshlrev_b64 v[28:29], 15, v[28:29]
	v_lshlrev_b64 v[30:31], 15, v[30:31]
	v_lshlrev_b64 v[32:33], 15, v[32:33]
	v_lshlrev_b64 v[34:35], 15, v[34:35]
	v_lshlrev_b64 v[36:37], 15, v[36:37]
	v_lshlrev_b64 v[38:39], 15, v[38:39]
	v_lshlrev_b64 v[40:41], 15, v[40:41]
	v_lshlrev_b64 v[42:43], 15, v[42:43]
	v_lshlrev_b64 v[44:45], 15, v[44:45]
	v_lshlrev_b64 v[46:47], 15, v[46:47]
	v_lshlrev_b64 v[48:49], 15, v[48:49]
	v_lshlrev_b64 v[50:51], 15, v[50:51]
	v_lshlrev_b64 v[52:53], 15, v[52:53]
	v_lshlrev_b64 v[54:55], 15, v[54:55]
	v_lshlrev_b64 v[56:57], 15, v[56:57]
	v_lshlrev_b64 v[58:59], 15, v[58:59]
	v_lshlrev_b64 v[60:61], 15, v[60:61]
	v_lshlrev_b64 v[62:63], 15, v[62:63]
	v_lshlrev_b64 v[64:65], 15, v[64:65]
	v_lshlrev_b64 v[66:67], 15, v[66:67]
	v_lshlrev_b64 v[68:69], 15, v[68:69]
	v_lshlrev_b64 v[70:71], 15, v[70:71]
	v_lshlrev_b64 v[72:73], 15, v[72:73]
	v_lshlrev_b64 v[8:9], 15, v[8:9]
	v_lshl_add_u64 v[74:75], v[12:13], 0, v[78:79]
	v_lshl_add_u64 v[78:79], v[12:13], 0, v[80:81]
	v_lshl_add_u64 v[80:81], v[12:13], 0, v[82:83]
	v_lshl_add_u64 v[10:11], v[76:77], 0, v[10:11]
; __device__ __forceinline__ unsigned cvtpk(float lo, float hi) { f32x2_t v = {lo, hi}; bf16x2_t b = __builtin_convertvector(v, bf16x2_t); return __builtin_bit_cast(unsigned, b); }
; __device__ __forceinline__ float lg2gamma(int h) { return log2f(1.0f - exp2f(-5.0f - (float)h)); }
; __global__ void __launch_bounds__(512, 2) mk_fwd(Args a) {
;     ...
;         for (int idx = bid * 512 + tid; idx < 16 * 16384; idx += G * 512) {
;             const int bh = idx >> 14, ed = idx & 16383, h = bh & 7;
;             const float lg = lg2gamma(h), gm = exp2f(lg), gC = exp2f(128.0f * lg);
;             float v[32];
; #pragma unroll
;             for (int n = 0; n < 32; ++n) v[n] = STATE[(size_t)(bh * 32 + n) * 16384 + ed];
;             float run = 0.f;
; #pragma unroll
;             for (int n = 0; n < 32; ++n) { SPREV[(size_t)(bh * 32 + n) * 16384 + ed] = (bf16_t)(cvtpk(gm * run, 0.f) & 0xffffu); run = run * gC + v[n]; }
	v_lshl_add_u64 v[82:83], v[12:13], 0, v[84:85]
	v_lshl_add_u64 v[84:85], v[12:13], 0, v[86:87]
	v_lshl_add_u64 v[86:87], v[12:13], 0, v[88:89]
	v_lshl_add_u64 v[88:89], v[12:13], 0, v[90:91]
	v_lshl_add_u64 v[14:15], v[76:77], 0, v[14:15]
	v_lshl_add_u64 v[16:17], v[76:77], 0, v[16:17]
	v_lshl_add_u64 v[18:19], v[76:77], 0, v[18:19]
	v_lshl_add_u64 v[20:21], v[76:77], 0, v[20:21]
	v_lshl_add_u64 v[22:23], v[76:77], 0, v[22:23]
	v_lshl_add_u64 v[24:25], v[76:77], 0, v[24:25]
	v_lshl_add_u64 v[26:27], v[76:77], 0, v[26:27]
	v_lshl_add_u64 v[28:29], v[76:77], 0, v[28:29]
	v_lshl_add_u64 v[30:31], v[76:77], 0, v[30:31]
	v_lshl_add_u64 v[32:33], v[76:77], 0, v[32:33]
	v_lshl_add_u64 v[34:35], v[76:77], 0, v[34:35]
	v_lshl_add_u64 v[36:37], v[76:77], 0, v[36:37]
	v_lshl_add_u64 v[38:39], v[76:77], 0, v[38:39]
	v_lshl_add_u64 v[40:41], v[76:77], 0, v[40:41]
	v_lshl_add_u64 v[42:43], v[76:77], 0, v[42:43]
	v_lshl_add_u64 v[44:45], v[76:77], 0, v[44:45]
	v_lshl_add_u64 v[46:47], v[76:77], 0, v[46:47]
	v_lshl_add_u64 v[48:49], v[76:77], 0, v[48:49]
	v_lshl_add_u64 v[50:51], v[76:77], 0, v[50:51]
	v_lshl_add_u64 v[52:53], v[76:77], 0, v[52:53]
	v_lshl_add_u64 v[54:55], v[76:77], 0, v[54:55]
	v_lshl_add_u64 v[56:57], v[76:77], 0, v[56:57]
	v_lshl_add_u64 v[58:59], v[76:77], 0, v[58:59]
	v_lshl_add_u64 v[60:61], v[76:77], 0, v[60:61]
	v_lshl_add_u64 v[62:63], v[76:77], 0, v[62:63]
	v_lshl_add_u64 v[64:65], v[76:77], 0, v[64:65]
	v_lshl_add_u64 v[66:67], v[76:77], 0, v[66:67]
	v_lshl_add_u64 v[68:69], v[76:77], 0, v[68:69]
	v_lshl_add_u64 v[70:71], v[76:77], 0, v[70:71]
	v_lshl_add_u64 v[72:73], v[76:77], 0, v[72:73]
	v_lshl_add_u64 v[8:9], v[76:77], 0, v[8:9]
	v_lshl_add_u64 v[226:227], v[74:75], 0, s[100:101]
	global_load_dword v74, v[74:75], off
	global_load_dword v193, v[226:227], off
	s_nop 0
	v_lshl_add_u64 v[224:225], v[78:79], 0, s[100:101]
	global_load_dword v75, v[78:79], off
	global_load_dword v194, v[224:225], off
	v_lshl_add_u64 v[226:227], v[80:81], 0, s[100:101]
	global_load_dword v76, v[80:81], off
	global_load_dword v195, v[226:227], off
	v_lshl_add_u64 v[224:225], v[82:83], 0, s[100:101]
	global_load_dword v77, v[82:83], off
	global_load_dword v196, v[224:225], off
	s_nop 0
	v_lshl_add_u64 v[226:227], v[84:85], 0, s[100:101]
	global_load_dword v78, v[84:85], off
	global_load_dword v197, v[226:227], off
	v_lshl_add_u64 v[224:225], v[86:87], 0, s[100:101]
	global_load_dword v79, v[86:87], off
	global_load_dword v198, v[224:225], off
	v_lshl_add_u64 v[226:227], v[88:89], 0, s[100:101]
	global_load_dword v80, v[88:89], off
	global_load_dword v199, v[226:227], off
	v_lshl_add_u64 v[90:91], v[12:13], 0, v[92:93]
	v_lshl_add_u64 v[92:93], v[12:13], 0, v[94:95]
	v_lshl_add_u64 v[94:95], v[12:13], 0, v[96:97]
	v_lshl_add_u64 v[96:97], v[12:13], 0, v[98:99]
	v_lshl_add_u64 v[98:99], v[12:13], 0, v[100:101]
	v_lshl_add_u64 v[100:101], v[12:13], 0, v[102:103]
	v_lshl_add_u64 v[102:103], v[12:13], 0, v[104:105]
	v_lshl_add_u64 v[104:105], v[12:13], 0, v[106:107]
	v_lshl_add_u64 v[106:107], v[12:13], 0, v[108:109]
	v_lshl_add_u64 v[108:109], v[12:13], 0, v[110:111]
	v_lshl_add_u64 v[110:111], v[12:13], 0, v[112:113]
	v_lshl_add_u64 v[112:113], v[12:13], 0, v[114:115]
	v_lshl_add_u64 v[114:115], v[12:13], 0, v[116:117]
	v_lshl_add_u64 v[116:117], v[12:13], 0, v[118:119]
	v_lshl_add_u64 v[118:119], v[12:13], 0, v[120:121]
	v_lshl_add_u64 v[120:121], v[12:13], 0, v[124:125]
	v_lshl_add_u64 v[124:125], v[12:13], 0, v[126:127]
	v_lshl_add_u64 v[126:127], v[12:13], 0, v[130:131]
	v_lshl_add_u64 v[130:131], v[12:13], 0, v[132:133]
	v_lshl_add_u64 v[132:133], v[12:13], 0, v[134:135]
	v_lshl_add_u64 v[134:135], v[12:13], 0, v[136:137]
	v_lshl_add_u64 v[136:137], v[12:13], 0, v[138:139]
	v_lshl_add_u64 v[12:13], v[12:13], 0, v[140:141]
	v_lshl_add_u64 v[224:225], v[90:91], 0, s[100:101]
	global_load_dword v81, v[90:91], off
	global_load_dword v200, v[224:225], off
	v_lshl_add_u64 v[226:227], v[92:93], 0, s[100:101]
	global_load_dword v82, v[92:93], off
	global_load_dword v201, v[226:227], off
	v_lshl_add_u64 v[224:225], v[94:95], 0, s[100:101]
	global_load_dword v83, v[94:95], off
	global_load_dword v202, v[224:225], off
	v_lshl_add_u64 v[226:227], v[96:97], 0, s[100:101]
	global_load_dword v84, v[96:97], off
	global_load_dword v203, v[226:227], off
	v_lshl_add_u64 v[224:225], v[98:99], 0, s[100:101]
	global_load_dword v85, v[98:99], off
	global_load_dword v204, v[224:225], off
	v_lshl_add_u64 v[226:227], v[100:101], 0, s[100:101]
	global_load_dword v86, v[100:101], off
	global_load_dword v205, v[226:227], off
	v_lshl_add_u64 v[224:225], v[102:103], 0, s[100:101]
	global_load_dword v87, v[102:103], off
	global_load_dword v206, v[224:225], off
	v_lshl_add_u64 v[226:227], v[104:105], 0, s[100:101]
	global_load_dword v88, v[104:105], off
	global_load_dword v207, v[226:227], off
	v_lshl_add_u64 v[224:225], v[106:107], 0, s[100:101]
	global_load_dword v89, v[106:107], off
	global_load_dword v208, v[224:225], off
	v_lshl_add_u64 v[226:227], v[108:109], 0, s[100:101]
	global_load_dword v90, v[108:109], off
	global_load_dword v209, v[226:227], off
	v_lshl_add_u64 v[224:225], v[110:111], 0, s[100:101]
	global_load_dword v91, v[110:111], off
	global_load_dword v210, v[224:225], off
	v_lshl_add_u64 v[226:227], v[112:113], 0, s[100:101]
	global_load_dword v92, v[112:113], off
	global_load_dword v211, v[226:227], off
	v_lshl_add_u64 v[224:225], v[114:115], 0, s[100:101]
	global_load_dword v93, v[114:115], off
	global_load_dword v212, v[224:225], off
	v_lshl_add_u64 v[226:227], v[116:117], 0, s[100:101]
	global_load_dword v94, v[116:117], off
	global_load_dword v213, v[226:227], off
; __device__ __forceinline__ unsigned cvtpk(float lo, float hi) { f32x2_t v = {lo, hi}; bf16x2_t b = __builtin_convertvector(v, bf16x2_t); return __builtin_bit_cast(unsigned, b); }
; __device__ __forceinline__ float lg2gamma(int h) { return log2f(1.0f - exp2f(-5.0f - (float)h)); }
; __global__ void __launch_bounds__(512, 2) mk_fwd(Args a) {
;     ...
;         for (int idx = bid * 512 + tid; idx < 16 * 16384; idx += G * 512) {
;             const int bh = idx >> 14, ed = idx & 16383, h = bh & 7;
;             const float lg = lg2gamma(h), gm = exp2f(lg), gC = exp2f(128.0f * lg);
;             float v[32];
; #pragma unroll
;             for (int n = 0; n < 32; ++n) v[n] = STATE[(size_t)(bh * 32 + n) * 16384 + ed];
;             float run = 0.f;
; #pragma unroll
;             for (int n = 0; n < 32; ++n) { SPREV[(size_t)(bh * 32 + n) * 16384 + ed] = (bf16_t)(cvtpk(gm * run, 0.f) & 0xffffu); run = run * gC + v[n]; }
	v_lshl_add_u64 v[224:225], v[118:119], 0, s[100:101]
	global_load_dword v95, v[118:119], off
	global_load_dword v214, v[224:225], off
	v_lshl_add_u64 v[226:227], v[120:121], 0, s[100:101]
	global_load_dword v96, v[120:121], off
	global_load_dword v215, v[226:227], off
	v_lshl_add_u64 v[224:225], v[124:125], 0, s[100:101]
	global_load_dword v97, v[124:125], off
	global_load_dword v216, v[224:225], off
	v_lshl_add_u64 v[226:227], v[126:127], 0, s[100:101]
	global_load_dword v98, v[126:127], off
	global_load_dword v217, v[226:227], off
	v_lshl_add_u64 v[224:225], v[130:131], 0, s[100:101]
	global_load_dword v99, v[130:131], off
	global_load_dword v218, v[224:225], off
	v_lshl_add_u64 v[226:227], v[132:133], 0, s[100:101]
	global_load_dword v100, v[132:133], off
	global_load_dword v219, v[226:227], off
	v_lshl_add_u64 v[224:225], v[134:135], 0, s[100:101]
	global_load_dword v101, v[134:135], off
	global_load_dword v220, v[224:225], off
	v_lshl_add_u64 v[226:227], v[136:137], 0, s[100:101]
	global_load_dword v102, v[136:137], off
	global_load_dword v221, v[226:227], off
	s_nop 0
	v_lshl_add_u64 v[224:225], v[12:13], 0, s[100:101]
	global_load_dword v12, v[12:13], off
	global_load_dword v222, v[224:225], off
	v_add_u32_e32 v4, s6, v4
	v_cmp_lt_i32_e32 vcc, s9, v4
	s_or_b64 s[4:5], vcc, s[4:5]
	v_cmp_gt_f32_e32 vcc, s7, v122
	s_nop 1
	v_cndmask_b32_e32 v2, 0, v5, vcc
	v_add_f32_e32 v2, v122, v2
	v_exp_f32_e32 v2, v2
	v_cndmask_b32_e32 v122, 0, v6, vcc
	v_ldexp_f32 v2, v2, v122
	v_sub_f32_e32 v2, 1.0, v2
	v_cmp_gt_f32_e32 vcc, s8, v2
	s_nop 1
	v_cndmask_b32_e64 v13, 0, 32, vcc
	v_ldexp_f32 v2, v2, v13
	v_log_f32_e32 v2, v2
	v_cndmask_b32_e32 v13, 0, v7, vcc
	v_sub_f32_e32 v2, v2, v13
	v_mul_f32_e32 v13, 0x43000000, v2
	v_cmp_gt_f32_e32 vcc, s7, v2
	s_nop 1
	v_cndmask_b32_e32 v103, 0, v5, vcc
	v_cndmask_b32_e32 v104, 0, v6, vcc
	v_cmp_gt_f32_e32 vcc, s7, v13
	v_add_f32_e32 v103, v2, v103
	v_exp_f32_e32 v103, v103
	v_cndmask_b32_e32 v13, 0, v5, vcc
	v_fmac_f32_e32 v13, 0x43000000, v2
	v_exp_f32_e32 v13, v13
	v_cndmask_b32_e32 v2, 0, v6, vcc
	v_ldexp_f32 v103, v103, v104
	v_ldexp_f32 v2, v13, v2
	v_mov_b32_e32 v228, v2
	v_lshl_add_u64 v[230:231], v[10:11], 0, s[98:99]
	v_mul_f32_e32 v13, 0, v103
	v_cvt_pk_bf16_f32 v13, v13, s0
	s_waitcnt vmcnt(0)
	v_fmac_f32_e32 v128, 0, v2
	global_store_short v[10:11], v13, off
	v_mul_f32_e32 v10, v103, v128
	v_cvt_pk_bf16_f32 v10, v10, s0
	global_store_short v[14:15], v10, off
	v_fmac_f32_e32 v74, v2, v128
	v_mul_f32_e32 v11, v103, v74
	v_fmac_f32_e32 v75, v2, v74
	v_cvt_pk_bf16_f32 v10, v11, s0
	v_mul_f32_e32 v11, v103, v75
	v_fmac_f32_e32 v76, v2, v75
	global_store_short v[16:17], v10, off
	v_cvt_pk_bf16_f32 v10, v11, s0
	v_mul_f32_e32 v11, v103, v76
	v_fmac_f32_e32 v77, v2, v76
	global_store_short v[18:19], v10, off
	v_cvt_pk_bf16_f32 v10, v11, s0
	v_mul_f32_e32 v11, v103, v77
	v_fmac_f32_e32 v78, v2, v77
	global_store_short v[20:21], v10, off
	v_cvt_pk_bf16_f32 v10, v11, s0
	v_mul_f32_e32 v11, v103, v78
	v_fmac_f32_e32 v79, v2, v78
	global_store_short v[22:23], v10, off
	v_cvt_pk_bf16_f32 v10, v11, s0
	v_mul_f32_e32 v11, v103, v79
	v_fmac_f32_e32 v80, v2, v79
	global_store_short v[24:25], v10, off
	v_cvt_pk_bf16_f32 v10, v11, s0
	v_mul_f32_e32 v11, v103, v80
	v_fmac_f32_e32 v81, v2, v80
	global_store_short v[26:27], v10, off
	v_cvt_pk_bf16_f32 v10, v11, s0
	v_mul_f32_e32 v11, v103, v81
	v_fmac_f32_e32 v82, v2, v81
	global_store_short v[28:29], v10, off
	v_cvt_pk_bf16_f32 v10, v11, s0
	v_mul_f32_e32 v11, v103, v82
	v_fmac_f32_e32 v83, v2, v82
	global_store_short v[30:31], v10, off
	v_cvt_pk_bf16_f32 v10, v11, s0
	v_mul_f32_e32 v11, v103, v83
	v_fmac_f32_e32 v84, v2, v83
	global_store_short v[32:33], v10, off
	v_cvt_pk_bf16_f32 v10, v11, s0
	v_mul_f32_e32 v11, v103, v84
	v_fmac_f32_e32 v85, v2, v84
	global_store_short v[34:35], v10, off
	v_cvt_pk_bf16_f32 v10, v11, s0
	v_mul_f32_e32 v11, v103, v85
	v_fmac_f32_e32 v86, v2, v85
	global_store_short v[36:37], v10, off
	v_cvt_pk_bf16_f32 v10, v11, s0
	v_mul_f32_e32 v11, v103, v86
	v_fmac_f32_e32 v87, v2, v86
	global_store_short v[38:39], v10, off
	v_cvt_pk_bf16_f32 v10, v11, s0
	v_mul_f32_e32 v11, v103, v87
	v_fmac_f32_e32 v88, v2, v87
	global_store_short v[40:41], v10, off
	v_cvt_pk_bf16_f32 v10, v11, s0
	v_mul_f32_e32 v11, v103, v88
	v_fmac_f32_e32 v89, v2, v88
	global_store_short v[42:43], v10, off
	v_cvt_pk_bf16_f32 v10, v11, s0
	v_mul_f32_e32 v11, v103, v89
	v_fmac_f32_e32 v90, v2, v89
	global_store_short v[44:45], v10, off
	v_cvt_pk_bf16_f32 v10, v11, s0
	v_mul_f32_e32 v11, v103, v90
	v_fmac_f32_e32 v91, v2, v90
	global_store_short v[46:47], v10, off
	v_cvt_pk_bf16_f32 v10, v11, s0
	v_mul_f32_e32 v11, v103, v91
	v_fmac_f32_e32 v92, v2, v91
	global_store_short v[48:49], v10, off
	v_cvt_pk_bf16_f32 v10, v11, s0
	v_mul_f32_e32 v11, v103, v92
	v_fmac_f32_e32 v93, v2, v92
	global_store_short v[50:51], v10, off
	v_cvt_pk_bf16_f32 v10, v11, s0
	v_mul_f32_e32 v11, v103, v93
	v_fmac_f32_e32 v94, v2, v93
	global_store_short v[52:53], v10, off
	v_cvt_pk_bf16_f32 v10, v11, s0
	v_mul_f32_e32 v11, v103, v94
	v_fmac_f32_e32 v95, v2, v94
	global_store_short v[54:55], v10, off
	v_cvt_pk_bf16_f32 v10, v11, s0
	v_mul_f32_e32 v11, v103, v95
	v_fmac_f32_e32 v96, v2, v95
	global_store_short v[56:57], v10, off
	v_cvt_pk_bf16_f32 v10, v11, s0
	v_mul_f32_e32 v11, v103, v96
	v_fmac_f32_e32 v97, v2, v96
	global_store_short v[58:59], v10, off
	v_cvt_pk_bf16_f32 v10, v11, s0
	v_mul_f32_e32 v11, v103, v97
	v_fmac_f32_e32 v98, v2, v97
	global_store_short v[60:61], v10, off
	v_cvt_pk_bf16_f32 v10, v11, s0
	v_mul_f32_e32 v11, v103, v98
	v_fmac_f32_e32 v99, v2, v98
	global_store_short v[62:63], v10, off
; __device__ __forceinline__ unsigned cvtpk(float lo, float hi) { f32x2_t v = {lo, hi}; bf16x2_t b = __builtin_convertvector(v, bf16x2_t); return __builtin_bit_cast(unsigned, b); }
; __device__ __forceinline__ float lg2gamma(int h) { return log2f(1.0f - exp2f(-5.0f - (float)h)); }
; __global__ void __launch_bounds__(512, 2) mk_fwd(Args a) {
;     ...
;         for (int idx = bid * 512 + tid; idx < 16 * 16384; idx += G * 512) {
;             const int bh = idx >> 14, ed = idx & 16383, h = bh & 7;
;             const float lg = lg2gamma(h), gm = exp2f(lg), gC = exp2f(128.0f * lg);
;             float v[32];
; #pragma unroll
;             for (int n = 0; n < 32; ++n) v[n] = STATE[(size_t)(bh * 32 + n) * 16384 + ed];
;             float run = 0.f;
; #pragma unroll
;             for (int n = 0; n < 32; ++n) { SPREV[(size_t)(bh * 32 + n) * 16384 + ed] = (bf16_t)(cvtpk(gm * run, 0.f) & 0xffffu); run = run * gC + v[n]; }
	v_cvt_pk_bf16_f32 v10, v11, s0
	v_mul_f32_e32 v11, v103, v99
	v_fmac_f32_e32 v100, v2, v99
	global_store_short v[64:65], v10, off
	v_cvt_pk_bf16_f32 v10, v11, s0
	v_mul_f32_e32 v11, v103, v100
	v_fmac_f32_e32 v101, v2, v100
	global_store_short v[66:67], v10, off
	v_cvt_pk_bf16_f32 v10, v11, s0
	v_mul_f32_e32 v11, v103, v101
	v_fmac_f32_e32 v102, v2, v101
	global_store_short v[68:69], v10, off
	v_cvt_pk_bf16_f32 v10, v11, s0
	v_mul_f32_e32 v11, v103, v102
	v_fmac_f32_e32 v12, v2, v102
	global_store_short v[70:71], v10, off
	v_cvt_pk_bf16_f32 v2, v11, s0
	v_mul_f32_e32 v10, v103, v12
	global_store_short v[72:73], v2, off
	v_cvt_pk_bf16_f32 v2, v10, s0
	global_store_short v[8:9], v2, off
	v_mul_f32_e32 v13, 0, v103
	v_cvt_pk_bf16_f32 v13, v13, s0
	v_fmac_f32_e32 v192, 0, v228
	global_store_short v[230:231], v13, off
	v_mul_f32_e32 v10, v103, v192
	v_cvt_pk_bf16_f32 v10, v10, s0
	v_lshl_add_u64 v[226:227], v[14:15], 0, s[98:99]
	global_store_short v[226:227], v10, off
	v_fmac_f32_e32 v193, v228, v192
	v_mul_f32_e32 v11, v103, v193
	v_fmac_f32_e32 v194, v228, v193
	v_cvt_pk_bf16_f32 v10, v11, s0
	v_mul_f32_e32 v11, v103, v194
	v_fmac_f32_e32 v195, v228, v194
	v_lshl_add_u64 v[224:225], v[16:17], 0, s[98:99]
	global_store_short v[224:225], v10, off
	v_cvt_pk_bf16_f32 v10, v11, s0
	v_mul_f32_e32 v11, v103, v195
	v_fmac_f32_e32 v196, v228, v195
	v_lshl_add_u64 v[226:227], v[18:19], 0, s[98:99]
	global_store_short v[226:227], v10, off
	v_cvt_pk_bf16_f32 v10, v11, s0
	v_mul_f32_e32 v11, v103, v196
	v_fmac_f32_e32 v197, v228, v196
	v_lshl_add_u64 v[224:225], v[20:21], 0, s[98:99]
	global_store_short v[224:225], v10, off
	v_cvt_pk_bf16_f32 v10, v11, s0
	v_mul_f32_e32 v11, v103, v197
	v_fmac_f32_e32 v198, v228, v197
	v_lshl_add_u64 v[226:227], v[22:23], 0, s[98:99]
	global_store_short v[226:227], v10, off
	v_cvt_pk_bf16_f32 v10, v11, s0
	v_mul_f32_e32 v11, v103, v198
	v_fmac_f32_e32 v199, v228, v198
	v_lshl_add_u64 v[224:225], v[24:25], 0, s[98:99]
	global_store_short v[224:225], v10, off
	v_cvt_pk_bf16_f32 v10, v11, s0
	v_mul_f32_e32 v11, v103, v199
	v_fmac_f32_e32 v200, v228, v199
	v_lshl_add_u64 v[226:227], v[26:27], 0, s[98:99]
	global_store_short v[226:227], v10, off
	v_cvt_pk_bf16_f32 v10, v11, s0
	v_mul_f32_e32 v11, v103, v200
	v_fmac_f32_e32 v201, v228, v200
	v_lshl_add_u64 v[224:225], v[28:29], 0, s[98:99]
	global_store_short v[224:225], v10, off
	v_cvt_pk_bf16_f32 v10, v11, s0
	v_mul_f32_e32 v11, v103, v201
	v_fmac_f32_e32 v202, v228, v201
	v_lshl_add_u64 v[226:227], v[30:31], 0, s[98:99]
	global_store_short v[226:227], v10, off
	v_cvt_pk_bf16_f32 v10, v11, s0
	v_mul_f32_e32 v11, v103, v202
	v_fmac_f32_e32 v203, v228, v202
	v_lshl_add_u64 v[224:225], v[32:33], 0, s[98:99]
	global_store_short v[224:225], v10, off
	v_cvt_pk_bf16_f32 v10, v11, s0
	v_mul_f32_e32 v11, v103, v203
	v_fmac_f32_e32 v204, v228, v203
	v_lshl_add_u64 v[226:227], v[34:35], 0, s[98:99]
	global_store_short v[226:227], v10, off
	v_cvt_pk_bf16_f32 v10, v11, s0
	v_mul_f32_e32 v11, v103, v204
	v_fmac_f32_e32 v205, v228, v204
	v_lshl_add_u64 v[224:225], v[36:37], 0, s[98:99]
	global_store_short v[224:225], v10, off
	v_cvt_pk_bf16_f32 v10, v11, s0
	v_mul_f32_e32 v11, v103, v205
	v_fmac_f32_e32 v206, v228, v205
	v_lshl_add_u64 v[226:227], v[38:39], 0, s[98:99]
	global_store_short v[226:227], v10, off
	v_cvt_pk_bf16_f32 v10, v11, s0
	v_mul_f32_e32 v11, v103, v206
	v_fmac_f32_e32 v207, v228, v206
	v_lshl_add_u64 v[224:225], v[40:41], 0, s[98:99]
	global_store_short v[224:225], v10, off
	v_cvt_pk_bf16_f32 v10, v11, s0
	v_mul_f32_e32 v11, v103, v207
	v_fmac_f32_e32 v208, v228, v207
	v_lshl_add_u64 v[226:227], v[42:43], 0, s[98:99]
	global_store_short v[226:227], v10, off
	v_cvt_pk_bf16_f32 v10, v11, s0
	v_mul_f32_e32 v11, v103, v208
	v_fmac_f32_e32 v209, v228, v208
	v_lshl_add_u64 v[224:225], v[44:45], 0, s[98:99]
	global_store_short v[224:225], v10, off
	v_cvt_pk_bf16_f32 v10, v11, s0
	v_mul_f32_e32 v11, v103, v209
	v_fmac_f32_e32 v210, v228, v209
	v_lshl_add_u64 v[226:227], v[46:47], 0, s[98:99]
	global_store_short v[226:227], v10, off
	v_cvt_pk_bf16_f32 v10, v11, s0
	v_mul_f32_e32 v11, v103, v210
	v_fmac_f32_e32 v211, v228, v210
	v_lshl_add_u64 v[224:225], v[48:49], 0, s[98:99]
	global_store_short v[224:225], v10, off
	v_cvt_pk_bf16_f32 v10, v11, s0
	v_mul_f32_e32 v11, v103, v211
	v_fmac_f32_e32 v212, v228, v211
	v_lshl_add_u64 v[226:227], v[50:51], 0, s[98:99]
	global_store_short v[226:227], v10, off
	v_cvt_pk_bf16_f32 v10, v11, s0
	v_mul_f32_e32 v11, v103, v212
	v_fmac_f32_e32 v213, v228, v212
	v_lshl_add_u64 v[224:225], v[52:53], 0, s[98:99]
	global_store_short v[224:225], v10, off
	v_cvt_pk_bf16_f32 v10, v11, s0
	v_mul_f32_e32 v11, v103, v213
	v_fmac_f32_e32 v214, v228, v213
	v_lshl_add_u64 v[226:227], v[54:55], 0, s[98:99]
	global_store_short v[226:227], v10, off
	v_cvt_pk_bf16_f32 v10, v11, s0
	v_mul_f32_e32 v11, v103, v214
	v_fmac_f32_e32 v215, v228, v214
	v_lshl_add_u64 v[224:225], v[56:57], 0, s[98:99]
	global_store_short v[224:225], v10, off
	v_cvt_pk_bf16_f32 v10, v11, s0
	v_mul_f32_e32 v11, v103, v215
	v_fmac_f32_e32 v216, v228, v215
	v_lshl_add_u64 v[226:227], v[58:59], 0, s[98:99]
	global_store_short v[226:227], v10, off
	v_cvt_pk_bf16_f32 v10, v11, s0
	v_mul_f32_e32 v11, v103, v216
	v_fmac_f32_e32 v217, v228, v216
	v_lshl_add_u64 v[224:225], v[60:61], 0, s[98:99]
	global_store_short v[224:225], v10, off
	v_cvt_pk_bf16_f32 v10, v11, s0
	v_mul_f32_e32 v11, v103, v217
	v_fmac_f32_e32 v218, v228, v217
	v_lshl_add_u64 v[226:227], v[62:63], 0, s[98:99]
	global_store_short v[226:227], v10, off
	v_cvt_pk_bf16_f32 v10, v11, s0
	v_mul_f32_e32 v11, v103, v218
	v_fmac_f32_e32 v219, v228, v218
	v_lshl_add_u64 v[224:225], v[64:65], 0, s[98:99]
	global_store_short v[224:225], v10, off
	v_cvt_pk_bf16_f32 v10, v11, s0
	v_mul_f32_e32 v11, v103, v219
	v_fmac_f32_e32 v220, v228, v219
	v_lshl_add_u64 v[226:227], v[66:67], 0, s[98:99]
	global_store_short v[226:227], v10, off
	v_cvt_pk_bf16_f32 v10, v11, s0
	v_mul_f32_e32 v11, v103, v220
	v_fmac_f32_e32 v221, v228, v220
	v_lshl_add_u64 v[224:225], v[68:69], 0, s[98:99]
	global_store_short v[224:225], v10, off
	v_cvt_pk_bf16_f32 v10, v11, s0
	v_mul_f32_e32 v11, v103, v221
	v_fmac_f32_e32 v222, v228, v221
	v_lshl_add_u64 v[226:227], v[70:71], 0, s[98:99]
	global_store_short v[226:227], v10, off
	v_cvt_pk_bf16_f32 v2, v11, s0
	v_mul_f32_e32 v10, v103, v222
	v_lshl_add_u64 v[224:225], v[72:73], 0, s[98:99]
	global_store_short v[224:225], v2, off
	v_cvt_pk_bf16_f32 v2, v10, s0
	v_lshl_add_u64 v[226:227], v[8:9], 0, s[98:99]
	global_store_short v[226:227], v2, off
	s_andn2_b64 exec, exec, s[4:5]
